# tile scheduler: generic division by gsz (always 8) replaced by shift/mask in all GEMM tile headers (on v42 peel)
# baseline (speedup 1.0000x reference)
;     __device__ bool next(int i, Unit& u) const {
;         const long L = (long)i * G + c; if (L >= nwg) return false;
;         int wgid = (int)L; { const int q = nwg / NXCD, r = nwg % NXCD, xcd = wgid % NXCD, off = wgid / NXCD; wgid = (xcd < r ? xcd * (q + 1) : r * (q + 1) + (xcd - r) * q) + off; }
;         const int nig = WGM * nN, gid = wgid / nig, fm = gid * WGM, gsz = (nM - fm) < WGM ? (nM - fm) : WGM;
;         u.pm = fm + ((wgid % nig) % gsz); u.pn = (wgid % nig) / gsz; return true;
;     }
.LBB0_229:
	s_add_i32 s34, s34, 1
	s_mul_i32 s4, s34, s37
	s_mul_hi_u32 s5, s34, s90
	s_add_i32 s5, s5, s4
	s_mul_i32 s4, s34, s90
	s_add_u32 s18, s4, s2
	s_addc_u32 s19, s5, s28
	v_cmp_gt_i64_e32 vcc, s[18:19], v[142:143]
	v_cmp_lt_i64_e64 s[4:5], s[18:19], v[140:141]
	s_cbranch_vccnz .LBB0_231
	s_ashr_i32 s14, s18, 31
	s_lshr_b32 s14, s14, 29
	s_add_i32 s14, s18, s14
	s_ashr_i32 s15, s14, 3
	s_and_b32 s14, s14, -8
	s_sub_i32 s14, s18, s14
	s_cmp_lt_i32 s14, 0
	s_cselect_b32 s16, s29, 0x140
	s_mul_i32 s14, s14, s16
	s_add_i32 s14, s14, s15
	s_mul_hi_i32 s15, s14, 0x66666667
	s_lshr_b32 s16, s15, 31
	s_ashr_i32 s15, s15, 5
	s_add_i32 s15, s15, s16
	s_lshl_b32 s16, s15, 3
	s_mulk_i32 s15, 0x50
	s_sub_i32 s15, s14, s15
	s_lshr_b32 s14, s15, 3
	s_and_b32 s15, s15, 7
	s_add_i32 s16, s16, s15

;     __device__ bool next(int i, Unit& u) const {
;         const long L = (long)i * G + c; if (L >= nwg) return false;
;         int wgid = (int)L; { const int q = nwg / NXCD, r = nwg % NXCD, xcd = wgid % NXCD, off = wgid / NXCD; wgid = (xcd < r ? xcd * (q + 1) : r * (q + 1) + (xcd - r) * q) + off; }
;         const int nig = WGM * nN, gid = wgid / nig, fm = gid * WGM, gsz = (nM - fm) < WGM ? (nM - fm) : WGM;
;         u.pm = fm + ((wgid % nig) % gsz); u.pn = (wgid % nig) / gsz; return true;
;     }
.LBB0_659:
	v_mov_b64_e32 v[0:1], 0x300
	v_cmp_gt_i64_e32 vcc, s[20:21], v[146:147]
	v_cmp_lt_i64_e64 s[6:7], s[20:21], v[0:1]
	s_cbranch_vccnz .LBB0_661
	s_ashr_i32 s4, s20, 31
	s_lshr_b32 s4, s4, 29
	s_add_i32 s4, s20, s4
	s_ashr_i32 s5, s4, 3
	s_and_b32 s4, s4, -8
	s_sub_i32 s4, s20, s4
	s_cmp_lt_i32 s4, 0
	s_cselect_b32 s30, s49, 0x60
	s_mul_i32 s4, s4, s30
	s_add_i32 s4, s4, s5
	s_mul_hi_i32 s5, s4, 0x2aaaaaab
	s_lshr_b32 s30, s5, 31
	s_ashr_i32 s5, s5, 2
	s_add_i32 s5, s5, s30
	s_lshl_b32 s30, s5, 3
	s_mul_i32 s5, s5, 24
	s_sub_i32 s4, s4, s5
	s_lshr_b32 s62, s4, 3
	s_and_b32 s4, s4, 7
	s_add_i32 s63, s30, s4

;     __device__ bool next(int i, Unit& u) const {
;         const long L = (long)i * G + c; if (L >= nwg) return false;
;         int wgid = (int)L; { const int q = nwg / NXCD, r = nwg % NXCD, xcd = wgid % NXCD, off = wgid / NXCD; wgid = (xcd < r ? xcd * (q + 1) : r * (q + 1) + (xcd - r) * q) + off; }
;         const int nig = WGM * nN, gid = wgid / nig, fm = gid * WGM, gsz = (nM - fm) < WGM ? (nM - fm) : WGM;
;         u.pm = fm + ((wgid % nig) % gsz); u.pn = (wgid % nig) / gsz; return true;
;     }
.LBB0_701:
	v_mov_b64_e32 v[0:1], 0x600
	v_cmp_lt_i64_e64 s[4:5], s[14:15], v[0:1]
	v_mov_b64_e32 v[0:1], 0x5ff
	v_cmp_gt_i64_e32 vcc, s[14:15], v[0:1]
	s_cbranch_vccnz .LBB0_703
	s_ashr_i32 s22, s14, 31
	s_lshr_b32 s22, s22, 29
	s_add_i32 s22, s14, s22
	s_ashr_i32 s23, s22, 3
	s_and_b32 s22, s22, -8
	s_sub_i32 s22, s14, s22
	s_cmp_lt_i32 s22, 0
	s_cselect_b32 s24, s48, 0xc0
	s_mul_i32 s22, s22, s24
	s_add_i32 s22, s22, s23
	s_mul_hi_i32 s23, s22, 0x2aaaaaab
	s_lshr_b32 s24, s23, 31
	s_ashr_i32 s23, s23, 3
	s_add_i32 s23, s23, s24
	s_lshl_b32 s24, s23, 3
	s_mul_i32 s23, s23, 48
	s_sub_i32 s23, s22, s23
	s_lshr_b32 s22, s23, 3
	s_and_b32 s23, s23, 7
	s_add_i32 s24, s24, s23

;     __device__ bool next(int i, Unit& u) const {
;         const long L = (long)i * G + c; if (L >= nwg) return false;
;         int wgid = (int)L; { const int q = nwg / NXCD, r = nwg % NXCD, xcd = wgid % NXCD, off = wgid / NXCD; wgid = (xcd < r ? xcd * (q + 1) : r * (q + 1) + (xcd - r) * q) + off; }
;         const int nig = WGM * nN, gid = wgid / nig, fm = gid * WGM, gsz = (nM - fm) < WGM ? (nM - fm) : WGM;
;         u.pm = fm + ((wgid % nig) % gsz); u.pn = (wgid % nig) / gsz; return true;
;     }
.LBB0_915:
	s_ashr_i32 s24, s26, 3
	s_add_i32 s24, s28, s24
	s_ashr_i32 s25, s24, 31
	s_lshr_b32 s25, s25, 27
	s_add_i32 s25, s24, s25
	s_ashr_i32 s26, s25, 5
	s_lshl_b32 s26, s26, 3
	s_andn2_b32 s25, s25, 31
	s_sub_i32 s25, s24, s25
	s_lshr_b32 s24, s25, 3
	s_and_b32 s25, s25, 7
	s_add_i32 s26, s26, s25

;     __device__ bool next(int i, Unit& u) const {
;         const long L = (long)i * G + c; if (L >= nwg) return false;
;         int wgid = (int)L; { const int q = nwg / NXCD, r = nwg % NXCD, xcd = wgid % NXCD, off = wgid / NXCD; wgid = (xcd < r ? xcd * (q + 1) : r * (q + 1) + (xcd - r) * q) + off; }
;         const int nig = WGM * nN, gid = wgid / nig, fm = gid * WGM, gsz = (nM - fm) < WGM ? (nM - fm) : WGM;
;         u.pm = fm + ((wgid % nig) % gsz); u.pn = (wgid % nig) / gsz; return true;
;     }
.LBB0_1049:
	s_add_i32 s34, s34, 1
	s_mul_i32 s4, s34, s37
	s_mul_hi_u32 s5, s34, s90
	s_add_i32 s5, s5, s4
	s_mul_i32 s4, s34, s90
	s_add_u32 s16, s4, s2
	s_addc_u32 s17, s5, s28
	v_cmp_gt_i64_e32 vcc, s[16:17], v[142:143]
	v_cmp_lt_i64_e64 s[4:5], s[16:17], v[140:141]
	s_cbranch_vccnz .LBB0_1051
	s_ashr_i32 s12, s16, 31
	s_lshr_b32 s12, s12, 29
	s_add_i32 s12, s16, s12
	s_ashr_i32 s13, s12, 3
	s_and_b32 s12, s12, -8
	s_sub_i32 s12, s16, s12
	s_cmp_lt_i32 s12, 0
	s_cselect_b32 s14, s29, 0x2c0
	s_mul_i32 s12, s12, s14
	s_add_i32 s12, s12, s13
	s_mul_hi_i32 s13, s12, 0x2e8ba2e9
	s_lshr_b32 s14, s13, 31
	s_ashr_i32 s13, s13, 5
	s_add_i32 s13, s13, s14
	s_lshl_b32 s14, s13, 3
	s_mulk_i32 s13, 0xb0
	s_sub_i32 s13, s12, s13
	s_lshr_b32 s12, s13, 3
	s_and_b32 s13, s13, 7
	s_add_i32 s14, s14, s13

;     __device__ bool next(int i, Unit& u) const {
;         const long L = (long)i * G + c; if (L >= nwg) return false;
;         int wgid = (int)L; { const int q = nwg / NXCD, r = nwg % NXCD, xcd = wgid % NXCD, off = wgid / NXCD; wgid = (xcd < r ? xcd * (q + 1) : r * (q + 1) + (xcd - r) * q) + off; }
;         const int nig = WGM * nN, gid = wgid / nig, fm = gid * WGM, gsz = (nM - fm) < WGM ? (nM - fm) : WGM;
;         u.pm = fm + ((wgid % nig) % gsz); u.pn = (wgid % nig) / gsz; return true;
;     }
.LBB0_1131:
	s_ashr_i32 s4, s24, 3
	s_add_i32 s4, s30, s4
	s_ashr_i32 s5, s4, 31
	s_lshr_b32 s5, s5, 27
	s_add_i32 s5, s4, s5
	s_ashr_i32 s24, s5, 5
	s_lshl_b32 s24, s24, 3
	s_andn2_b32 s5, s5, 31
	s_sub_i32 s4, s4, s5
	s_lshr_b32 s42, s4, 3
	s_and_b32 s4, s4, 7
	s_add_i32 s62, s24, s4

;     __device__ bool next(int i, Unit& u) const {
;         const long L = (long)i * G + c; if (L >= nwg) return false;
;         int wgid = (int)L; { const int q = nwg / NXCD, r = nwg % NXCD, xcd = wgid % NXCD, off = wgid / NXCD; wgid = (xcd < r ? xcd * (q + 1) : r * (q + 1) + (xcd - r) * q) + off; }
;         const int nig = WGM * nN, gid = wgid / nig, fm = gid * WGM, gsz = (nM - fm) < WGM ? (nM - fm) : WGM;
;         u.pm = fm + ((wgid % nig) % gsz); u.pn = (wgid % nig) / gsz; return true;
;     }
.LBB0_1277:
	s_ashr_i32 s7, s7, 3
	s_add_i32 s7, s25, s7
	s_ashr_i32 s22, s7, 31
	s_lshr_b32 s22, s22, 25
	s_add_i32 s22, s7, s22
	s_ashr_i32 s23, s22, 7
	s_lshl_b32 s23, s23, 3
	s_and_b32 s22, s22, 0xffffff80
	s_sub_i32 s7, s7, s22
	s_lshr_b32 s22, s7, 3
	s_and_b32 s7, s7, 7
	s_add_i32 s24, s23, s7

;     __device__ bool next(int i, Unit& u) const {
;         const long L = (long)i * G + c; if (L >= nwg) return false;
;         int wgid = (int)L; { const int q = nwg / NXCD, r = nwg % NXCD, xcd = wgid % NXCD, off = wgid / NXCD; wgid = (xcd < r ? xcd * (q + 1) : r * (q + 1) + (xcd - r) * q) + off; }
;         const int nig = WGM * nN, gid = wgid / nig, fm = gid * WGM, gsz = (nM - fm) < WGM ? (nM - fm) : WGM;
;         u.pm = fm + ((wgid % nig) % gsz); u.pn = (wgid % nig) / gsz; return true;
;     }
.LBB0_1475:
	s_ashr_i32 s22, s24, 3
	s_add_i32 s22, s26, s22
	s_ashr_i32 s23, s22, 31
	s_lshr_b32 s23, s23, 27
	s_add_i32 s23, s22, s23
	s_ashr_i32 s24, s23, 5
	s_lshl_b32 s24, s24, 3
	s_andn2_b32 s23, s23, 31
	s_sub_i32 s23, s22, s23
	s_lshr_b32 s22, s23, 3
	s_and_b32 s23, s23, 7
	s_add_i32 s24, s24, s23

;     __device__ bool next(int i, Unit& u) const {
;         const long L = (long)i * G + c; if (L >= nwg) return false;
;         int wgid = (int)L; { const int q = nwg / NXCD, r = nwg % NXCD, xcd = wgid % NXCD, off = wgid / NXCD; wgid = (xcd < r ? xcd * (q + 1) : r * (q + 1) + (xcd - r) * q) + off; }
;         const int nig = WGM * nN, gid = wgid / nig, fm = gid * WGM, gsz = (nM - fm) < WGM ? (nM - fm) : WGM;
;         u.pm = fm + ((wgid % nig) % gsz); u.pn = (wgid % nig) / gsz; return true;
;     }
.LBB0_1691:
	s_ashr_i32 s4, s24, 3
	s_add_i32 s4, s30, s4
	s_ashr_i32 s5, s4, 31
	s_lshr_b32 s5, s5, 27
	s_add_i32 s5, s4, s5
	s_ashr_i32 s24, s5, 5
	s_lshl_b32 s24, s24, 3
	s_andn2_b32 s5, s5, 31
	s_sub_i32 s4, s4, s5
	s_lshr_b32 s42, s4, 3
	s_and_b32 s4, s4, 7
	s_add_i32 s58, s24, s4
